# attention loop v2: first two K fragment reads before the transposed V reads; PV01 MFMAs lead the post-barrier staging writes/loads
# baseline (speedup 1.0000x reference)
; #define SBAR() __builtin_amdgcn_sched_barrier(0)
; template <int DA, int DB> __device__ __forceinline__ void pv2_issue(PvT& T, int vb) {
;   T.t[0] = tr_read<v_rd_off(DA, 0, 0)>(vb); T.t[1] = tr_read<v_rd_off(DA, 0, 1)>(vb); T.t[2] = tr_read<v_rd_off(DA, 1, 0)>(vb); T.t[3] = tr_read<v_rd_off(DA, 1, 1)>(vb);
;   T.t[4] = tr_read<v_rd_off(DA, 2, 0)>(vb); T.t[5] = tr_read<v_rd_off(DA, 2, 1)>(vb); T.t[6] = tr_read<v_rd_off(DA, 3, 0)>(vb); T.t[7] = tr_read<v_rd_off(DA, 3, 1)>(vb);
;   T.t[8] = tr_read<v_rd_off(DB, 0, 0)>(vb); T.t[9] = tr_read<v_rd_off(DB, 0, 1)>(vb); T.t[10] = tr_read<v_rd_off(DB, 1, 0)>(vb); T.t[11] = tr_read<v_rd_off(DB, 1, 1)>(vb);
;   T.t[12] = tr_read<v_rd_off(DB, 2, 0)>(vb); T.t[13] = tr_read<v_rd_off(DB, 2, 1)>(vb); T.t[14] = tr_read<v_rd_off(DB, 3, 0)>(vb); T.t[15] = tr_read<v_rd_off(DB, 3, 1)>(vb);
; }
; __device__ __forceinline__ void pv2_mma(f32x16& oa, f32x16& ob, const PvT& T, bf16x8 pa0, bf16x8 pa1, bf16x8 pa2, bf16x8 pa3) {
;   asm volatile("s_waitcnt lgkmcnt(0)" ::: "memory"); SBAR();
;     ...
;   oa = __builtin_amdgcn_mfma_f32_32x32x16_bf16(pa0, PK(T.t[0], T.t[1]), oa, 0, 0, 0);
;   ob = __builtin_amdgcn_mfma_f32_32x32x16_bf16(pa0, PK(T.t[8], T.t[9]), ob, 0, 0, 0);
;   oa = __builtin_amdgcn_mfma_f32_32x32x16_bf16(pa1, PK(T.t[2], T.t[3]), oa, 0, 0, 0);
;   ob = __builtin_amdgcn_mfma_f32_32x32x16_bf16(pa1, PK(T.t[10], T.t[11]), ob, 0, 0, 0);
;   oa = __builtin_amdgcn_mfma_f32_32x32x16_bf16(pa2, PK(T.t[4], T.t[5]), oa, 0, 0, 0);
; __device__ __forceinline__ void attn_dv256_body(const bf16* __restrict__ Qb, const bf16* __restrict__ Kh, const bf16* __restrict__ Vh,
;                                                 float* __restrict__ Ob, int seq, float kmax, char* lds) {
;     ...
;   for (int j = 0; j < NT; ++j) {
;     const int b = j & 1;
;     PvT T;
;     pv2_issue<2, 3>(T, vb0 + (b ^ 1) * 32768);
;     QKH(pn, b ^ 1);
;     float ps = 0.f;
; #pragma unroll
;     for (int r = 0; r < 16; ++r) { pc[r] = __builtin_amdgcn_exp2f(fmaf(pc[r], C, mC)); ps += pc[r]; }
;     l_reg += ps;
;     pv2_mma(o[2], o[3], T, q0, q1, q2, q3);
;     pv2_issue<0, 1>(T, vb0 + (b ^ 1) * 32768);
;     bf16x8 own0, own1; PK4(pc, 0, own0); PK4(pc, 8, own1);
;     *(bf16x8*)(XC0 + b * 16384 + ((wid * 2 + 0) * 64 + lane) * 16) = own0; *(bf16x8*)(XC0 + b * 16384 + ((wid * 2 + 1) * 64 + lane) * 16) = own1;
;     KWRITE(b);
;     pv2_mma(o[0], o[1], T, q0, q1, q2, q3);
.LBB0_910:
	s_and_b32 s1, s7, 1
	s_xor_b32 s22, s1, 1
	s_lshl_b32 s13, s22, 15
	v_lshl_add_u32 v246, s22, 14, v197
	v_fmamk_f32 v174, v64, 0x3e0293ee, v208
	v_fmamk_f32 v175, v65, 0x3e0293ee, v208
	v_fmamk_f32 v181, v66, 0x3e0293ee, v208
	v_fmamk_f32 v182, v67, 0x3e0293ee, v208
	v_add_u32_e32 v64, v246, v198
	ds_read_b128 v[64:67], v64
	v_fmamk_f32 v238, v68, 0x3e0293ee, v208
	v_add_u32_e32 v68, v246, v199
	ds_read_b128 v[230:233], v68
	v_add_u32_e32 v247, s13, v207
	ds_read_b64_tr_b16 v[152:153], v247 offset:0x400
	v_fmamk_f32 v239, v69, 0x3e0293ee, v208
	ds_read_b64_tr_b16 v[154:155], v247 offset:0xc00
	v_fmamk_f32 v240, v70, 0x3e0293ee, v208
	ds_read_b64_tr_b16 v[156:157], v247 offset:0x1400
	v_fmamk_f32 v241, v71, 0x3e0293ee, v208
	ds_read_b64_tr_b16 v[158:159], v247 offset:0x1c00
	v_fmamk_f32 v242, v72, 0x3e0293ee, v208
	ds_read_b64_tr_b16 v[160:161], v247 offset:0x2400
	v_fmamk_f32 v243, v73, 0x3e0293ee, v208
	ds_read_b64_tr_b16 v[162:163], v247 offset:0x2c00
	v_fmamk_f32 v244, v74, 0x3e0293ee, v208
	ds_read_b64_tr_b16 v[210:211], v247 offset:0x3400
	v_fmamk_f32 v245, v75, 0x3e0293ee, v208
	ds_read_b64_tr_b16 v[212:213], v247 offset:0x3c00
	v_fmamk_f32 v248, v76, 0x3e0293ee, v208
	ds_read_b64_tr_b16 v[214:215], v247 offset:0x600
	v_fmamk_f32 v249, v77, 0x3e0293ee, v208
	ds_read_b64_tr_b16 v[216:217], v247 offset:0xe00
	v_fmamk_f32 v250, v78, 0x3e0293ee, v208
	ds_read_b64_tr_b16 v[218:219], v247 offset:0x1600
	v_fmamk_f32 v173, v79, 0x3e0293ee, v208
	ds_read_b64_tr_b16 v[220:221], v247 offset:0x1e00
	ds_read_b64_tr_b16 v[222:223], v247 offset:0x2600
	ds_read_b64_tr_b16 v[224:225], v247 offset:0x2e00
	ds_read_b64_tr_b16 v[226:227], v247 offset:0x3600
	ds_read_b64_tr_b16 v[228:229], v247 offset:0x3e00
	s_waitcnt lgkmcnt(15)
	v_mfma_f32_32x32x16_bf16 v[64:79], v[64:67], v[80:83], 0
	v_add_u32_e32 v234, v246, v200
	v_exp_f32_e32 v174, v174
	v_exp_f32_e32 v175, v175
	v_exp_f32_e32 v181, v181
	v_exp_f32_e32 v182, v182
	v_exp_f32_e32 v238, v238
	v_exp_f32_e32 v239, v239
	s_waitcnt lgkmcnt(15)
	v_mfma_f32_32x32x16_bf16 v[64:79], v[230:233], v[84:87], v[64:79]
	ds_read_b128 v[230:233], v234
	v_add_u32_e32 v234, v246, v201
	ds_read_b128 v[234:237], v234
	v_exp_f32_e32 v240, v240
	v_exp_f32_e32 v241, v241
	v_exp_f32_e32 v242, v242
	v_exp_f32_e32 v243, v243
	s_waitcnt lgkmcnt(1)
	v_mfma_f32_32x32x16_bf16 v[64:79], v[230:233], v[88:91], v[64:79]
	v_add_u32_e32 v230, v246, v202
	ds_read_b128 v[230:233], v230
	v_exp_f32_e32 v244, v244
	v_exp_f32_e32 v245, v245
	v_exp_f32_e32 v248, v248
	v_exp_f32_e32 v249, v249
	v_exp_f32_e32 v250, v250
	s_waitcnt lgkmcnt(1)
	v_mfma_f32_32x32x16_bf16 v[64:79], v[234:237], v[92:95], v[64:79]
	v_add_u32_e32 v234, v246, v203
	ds_read_b128 v[234:237], v234
	v_exp_f32_e32 v173, v173
	s_waitcnt lgkmcnt(1)
	v_mfma_f32_32x32x16_bf16 v[64:79], v[230:233], v[96:99], v[64:79]
	v_add_u32_e32 v230, v246, v204
	ds_read_b128 v[230:233], v230
	s_waitcnt lgkmcnt(1)
	v_mfma_f32_32x32x16_bf16 v[64:79], v[234:237], v[100:103], v[64:79]
	v_add_f32_e32 v235, 0, v174
	v_add_f32_e32 v235, v175, v235
	v_add_u32_e32 v234, v246, v206
	v_add_f32_e32 v235, v181, v235
	v_add_f32_e32 v246, v182, v235
	ds_read_b128 v[234:237], v234
	s_waitcnt lgkmcnt(0)
	s_waitcnt lgkmcnt(1)
	v_mfma_f32_32x32x16_bf16 v[64:79], v[230:233], v[104:107], v[64:79]
	v_add_f32_e32 v230, v238, v246
	v_add_f32_e32 v230, v239, v230
	v_add_f32_e32 v230, v240, v230
	v_add_f32_e32 v230, v241, v230
	v_add_f32_e32 v230, v242, v230
	v_add_f32_e32 v230, v243, v230
	v_add_f32_e32 v230, v244, v230
	s_waitcnt lgkmcnt(0)
	v_mfma_f32_32x32x16_bf16 v[64:79], v[234:237], v[108:111], v[64:79]
	v_add_f32_e32 v230, v245, v230
	v_add_f32_e32 v230, v248, v230
	v_add_f32_e32 v230, v249, v230
	v_add_f32_e32 v230, v250, v230
	v_add_f32_e32 v230, v173, v230
	v_add_f32_e32 v192, v192, v230
	v_cvt_pk_bf16_f32 v241, v240, v241
	v_cvt_pk_bf16_f32 v240, v238, v239
	v_cvt_pk_bf16_f32 v239, v181, v182
	v_cvt_pk_bf16_f32 v238, v174, v175
	v_cvt_pk_bf16_f32 v242, v242, v243
	v_cvt_pk_bf16_f32 v243, v244, v245
	v_cvt_pk_bf16_f32 v244, v248, v249
	v_cvt_pk_bf16_f32 v245, v250, v173
	s_lshl_b32 s1, s1, 14
	s_add_i32 s1, s1, 0
	s_add_i32 s35, s1, 0x18000
	s_add_i32 s1, s1, 0x10000
	v_permlane32_swap_b32_e32 v238, v240
	v_permlane32_swap_b32_e32 v239, v241
	v_add3_u32 v173, s35, v209, v205
	v_permlane32_swap_b32_e32 v242, v244
	v_permlane32_swap_b32_e32 v243, v245
	ds_write_b128 v173, v[238:241]
	ds_write_b128 v173, v[242:245] offset:1024
	v_mfma_f32_32x32x16_bf16 v[32:47], v[144:147], v[152:155], v[32:47]
	v_mfma_f32_32x32x16_bf16 v[48:63], v[144:147], v[214:217], v[48:63]
	v_mfma_f32_32x32x16_bf16 v[32:47], v[148:151], v[156:159], v[32:47]
	v_mfma_f32_32x32x16_bf16 v[48:63], v[148:151], v[218:221], v[48:63]
	v_add_u32_e32 v173, s1, v195
	s_waitcnt vmcnt(1)
	ds_write_b128 v173, v[136:139]
	v_add_u32_e32 v136, s1, v196
	s_waitcnt vmcnt(0)
	ds_write_b128 v136, v[140:143]
	v_mfma_f32_32x32x16_bf16 v[32:47], v[132:135], v[160:163], v[32:47]
	v_mfma_f32_32x32x16_bf16 v[48:63], v[132:135], v[222:225], v[48:63]
	v_mfma_f32_32x32x16_bf16 v[32:47], v[128:131], v[210:213], v[32:47]
	ds_read_b64_tr_b16 v[210:211], v247 offset:0
	ds_read_b64_tr_b16 v[212:213], v247 offset:0x800
	ds_read_b64_tr_b16 v[214:215], v247 offset:0x1000
	ds_read_b64_tr_b16 v[216:217], v247 offset:0x1800
	ds_read_b64_tr_b16 v[218:219], v247 offset:0x2000
	ds_read_b64_tr_b16 v[220:221], v247 offset:0x2800
	ds_read_b64_tr_b16 v[222:223], v247 offset:0x3000
	ds_read_b64_tr_b16 v[224:225], v247 offset:0x3800
	v_mfma_f32_32x32x16_bf16 v[48:63], v[128:131], v[226:229], v[48:63]
	ds_read_b64_tr_b16 v[226:227], v247 offset:0x200
	ds_read_b64_tr_b16 v[228:229], v247 offset:0xa00
	ds_read_b64_tr_b16 v[230:231], v247 offset:0x1200
	ds_read_b64_tr_b16 v[232:233], v247 offset:0x1a00
	ds_read_b64_tr_b16 v[234:235], v247 offset:0x2200
	ds_read_b64_tr_b16 v[236:237], v247 offset:0x2a00
	ds_read_b64_tr_b16 v[160:161], v247 offset:0x3200
	ds_read_b64_tr_b16 v[162:163], v247 offset:0x3a00
	s_waitcnt lgkmcnt(0)
	s_add_i32 s1, s13, 0
	s_add_i32 s13, s7, 3
	s_add_i32 s22, s7, 2
	v_add_u32_e32 v136, s1, v193
	v_add_u32_e32 v137, s1, v194
	s_min_u32 s1, s13, s0
	s_min_u32 s13, s22, s0
	s_lshl_b32 s1, s1, 6
	s_lshl_b32 s13, s13, 6
	s_waitcnt lgkmcnt(0)
	s_barrier
; #define KLOAD(k0) do { kr0 = St::ld8(&Kh[(long)((k0) + sr) * LDK + sc]); kr1 = St::ld8(&Kh[(long)((k0) + 32 + sr) * LDK + sc]); } while (0)
; #define VLOAD(k0) do { vr0 = St::ld8(&Vh[(long)((k0) + sr) * LDK + sc]); vr1 = St::ld8(&Vh[(long)((k0) + 32 + sr) * LDK + sc]); \
;     vr2 = St::ld8(&Vh[(long)((k0) + sr) * LDK + 128 + sc]); vr3 = St::ld8(&Vh[(long)((k0) + 32 + sr) * LDK + 128 + sc]); } while (0)
; #define VWRITE(b) do { *(bf16x8*)(V_lds + ((b) * 2) * 16384 + vst0) = vr0; *(bf16x8*)(V_lds + ((b) * 2) * 16384 + vst1) = vr1; \
;     *(bf16x8*)(V_lds + ((b) * 2 + 1) * 16384 + vst1) = vr2; *(bf16x8*)(V_lds + ((b) * 2 + 1) * 16384 + vst0) = vr3; } while (0)
; __device__ __forceinline__ void attn_dv256_body(const bf16* __restrict__ Qb, const bf16* __restrict__ Kh, const bf16* __restrict__ Vh,
;                                                 float* __restrict__ Ob, int seq, float kmax, char* lds) {
;     ...
;     pv2_mma(o[0], o[1], T, q0, q1, q2, q3);
;     __syncthreads();
;     VWRITE(b ^ 1);
;     { const int kt = (j + 3 < NT) ? j + 3 : NT - 1, vt = (j + 2 < NT) ? j + 2 : NT - 1; KLOAD(kt * KVBLK); VLOAD(vt * KVBLK); }
;     q0 = own0; q1 = own1;
;     q2 = *(const bf16x8*)(XC0 + b * 16384 + (((wid ^ 4) * 2 + 0) * 64 + lane) * 16); q3 = *(const bf16x8*)(XC0 + b * 16384 + (((wid ^ 4) * 2 + 1) * 64 + lane) * 16);
;     pc = pn;
;   }
;   { PvT T; const int vl = vb0 + ((NT - 1) & 1) * 32768;
;     pv2_issue<2, 3>(T, vl); pv2_mma(o[2], o[3], T, q0, q1, q2, q3); pv2_issue<0, 1>(T, vl); pv2_mma(o[0], o[1], T, q0, q1, q2, q3); }
;   l_reg += __shfl_xor(l_reg, 32);
;   if (hi == 0) LI[kh * 128 + rg * 32 + r32] = l_reg;
	v_mfma_f32_32x32x16_bf16 v[0:15], v[144:147], v[210:213], v[0:15]
	ds_write_b128 v136, v[116:119]
	ds_write_b128 v137, v[112:115]
	v_mfma_f32_32x32x16_bf16 v[16:31], v[144:147], v[226:229], v[16:31]
	v_mov_b32_e32 v144, v238
	v_mov_b32_e32 v145, v239
	v_mov_b32_e32 v146, v240
	v_mov_b32_e32 v147, v241
	v_add_u32_e32 v112, s1, v189
	v_add_u32_e32 v114, s1, v190
	v_add_u32_e32 v116, s13, v189
	ds_write_b128 v137, v[120:123] offset:16384
	ds_write_b128 v136, v[124:127] offset:16384
	v_mfma_f32_32x32x16_bf16 v[0:15], v[148:151], v[214:217], v[0:15]
	v_add_u32_e32 v117, s13, v190
	v_mad_i64_i32 v[112:113], s[22:23], v112, s93, v[166:167]
	v_mad_i64_i32 v[114:115], s[22:23], v114, s93, v[166:167]
	v_mfma_f32_32x32x16_bf16 v[16:31], v[148:151], v[230:233], v[16:31]
	v_mov_b32_e32 v149, v243
	v_mov_b32_e32 v150, v244
	v_mov_b32_e32 v151, v245
	v_mad_i64_i32 v[120:121], s[22:23], v116, s93, v[168:169]
	v_mad_i64_i32 v[124:125], s[22:23], v117, s93, v[168:169]
	v_mfma_f32_32x32x16_bf16 v[0:15], v[132:135], v[218:221], v[0:15]
	global_load_dwordx4 v[136:139], v[112:113], off
	global_load_dwordx4 v[140:143], v[114:115], off
	v_mfma_f32_32x32x16_bf16 v[16:31], v[132:135], v[234:237], v[16:31]
	v_bitop3_b32 v132, v209, s95, v205 bitop3:0x36
	v_add_u32_e32 v148, s35, v132
	global_load_dwordx4 v[112:115], v[124:125], off
	global_load_dwordx4 v[116:119], v[120:121], off
	v_mfma_f32_32x32x16_bf16 v[0:15], v[128:131], v[222:225], v[0:15]
	global_load_dwordx4 v[120:123], v[120:121], off offset:256
	global_load_dwordx4 v[124:127], v[124:125], off offset:256
	s_add_i32 s7, s7, 1
	s_cmp_eq_u32 s6, s7
	v_mfma_f32_32x32x16_bf16 v[16:31], v[128:131], v[160:163], v[16:31]
	ds_read_b128 v[132:135], v148
	ds_read_b128 v[128:131], v148 offset:1024
	v_mov_b32_e32 v148, v242
	s_cbranch_scc0 .LBB0_910
	v_mov_b32_e32 v152, v238
	v_mov_b32_e32 v153, v239
	v_mov_b32_e32 v154, v240
	v_mov_b32_e32 v155, v241
	v_mov_b32_e32 v156, v242
	v_mov_b32_e32 v157, v243
	v_mov_b32_e32 v158, v244
	v_mov_b32_e32 v159, v245
	v_add_u32_e32 v96, 0x8000, v207
	ds_read_b64_tr_b16 v[64:65], v96 offset:0x400
	ds_read_b64_tr_b16 v[66:67], v96 offset:0xc00
	ds_read_b64_tr_b16 v[68:69], v96 offset:0x1400
	ds_read_b64_tr_b16 v[70:71], v96 offset:0x1c00
	ds_read_b64_tr_b16 v[72:73], v96 offset:0x2400
	ds_read_b64_tr_b16 v[74:75], v96 offset:0x2c00
	ds_read_b64_tr_b16 v[76:77], v96 offset:0x3400
	ds_read_b64_tr_b16 v[78:79], v96 offset:0x3c00
	ds_read_b64_tr_b16 v[80:81], v96 offset:0x600
	ds_read_b64_tr_b16 v[82:83], v96 offset:0xe00
	ds_read_b64_tr_b16 v[84:85], v96 offset:0x1600
	ds_read_b64_tr_b16 v[86:87], v96 offset:0x1e00
	ds_read_b64_tr_b16 v[88:89], v96 offset:0x2600
	ds_read_b64_tr_b16 v[90:91], v96 offset:0x2e00
	ds_read_b64_tr_b16 v[92:93], v96 offset:0x3600
	ds_read_b64_tr_b16 v[94:95], v96 offset:0x3e00
	s_waitcnt lgkmcnt(0)
	s_nop 0
	v_mfma_f32_32x32x16_bf16 v[32:47], v[152:155], v[64:67], v[32:47]
	ds_read_b64_tr_b16 v[64:65], v96 offset:0
	ds_read_b64_tr_b16 v[66:67], v96 offset:0x800
	v_mfma_f32_32x32x16_bf16 v[48:63], v[152:155], v[80:83], v[48:63]
	v_mfma_f32_32x32x16_bf16 v[32:47], v[156:159], v[68:71], v[32:47]
	ds_read_b64_tr_b16 v[68:69], v96 offset:0x1000
	ds_read_b64_tr_b16 v[70:71], v96 offset:0x1800
	v_mfma_f32_32x32x16_bf16 v[48:63], v[156:159], v[84:87], v[48:63]
	s_waitcnt lgkmcnt(1)
	v_mfma_f32_32x32x16_bf16 v[32:47], v[132:135], v[72:75], v[32:47]
	ds_read_b64_tr_b16 v[72:73], v96 offset:0x2000
	ds_read_b64_tr_b16 v[74:75], v96 offset:0x2800
	v_mfma_f32_32x32x16_bf16 v[48:63], v[132:135], v[88:91], v[48:63]
	s_waitcnt lgkmcnt(0)
	v_mfma_f32_32x32x16_bf16 v[32:47], v[128:131], v[76:79], v[32:47]
	ds_read_b64_tr_b16 v[76:77], v96 offset:0x3000
	ds_read_b64_tr_b16 v[78:79], v96 offset:0x3800
	ds_read_b64_tr_b16 v[80:81], v96 offset:0x200
	ds_read_b64_tr_b16 v[82:83], v96 offset:0xa00
	ds_read_b64_tr_b16 v[84:85], v96 offset:0x1200
	ds_read_b64_tr_b16 v[86:87], v96 offset:0x1a00
	ds_read_b64_tr_b16 v[88:89], v96 offset:0x2200
	v_mfma_f32_32x32x16_bf16 v[48:63], v[128:131], v[92:95], v[48:63]
	ds_read_b64_tr_b16 v[90:91], v96 offset:0x2a00
	ds_read_b64_tr_b16 v[92:93], v96 offset:0x3200
	ds_read_b64_tr_b16 v[94:95], v96 offset:0x3a00
	s_waitcnt lgkmcnt(0)
	v_mfma_f32_32x32x16_bf16 v[0:15], v[152:155], v[64:67], v[0:15]
	ds_bpermute_b32 v66, v188, v192
	v_cmp_gt_u32_e32 vcc, 32, v191
	v_lshlrev_b32_e32 v65, 2, v185
	v_lshlrev_b32_e32 v64, 2, v186
	v_mfma_f32_32x32x16_bf16 v[16:31], v[152:155], v[80:83], v[16:31]
	v_mfma_f32_32x32x16_bf16 v[0:15], v[156:159], v[68:71], v[0:15]
	v_mfma_f32_32x32x16_bf16 v[16:31], v[156:159], v[84:87], v[16:31]
	v_mfma_f32_32x32x16_bf16 v[0:15], v[132:135], v[72:75], v[0:15]
	v_mfma_f32_32x32x16_bf16 v[16:31], v[132:135], v[88:91], v[16:31]
	v_mfma_f32_32x32x16_bf16 v[0:15], v[128:131], v[76:79], v[0:15]
	v_mfma_f32_32x32x16_bf16 v[16:31], v[128:131], v[92:95], v[16:31]
	s_and_saveexec_b64 s[0:1], vcc
	s_cbranch_execz .LBB0_913
	s_add_i32 s6, 0, 0x20000
	v_lshl_add_u32 v67, v187, 9, s6
	v_add3_u32 v67, v67, v65, v64
	s_waitcnt lgkmcnt(0)
	v_add_f32_e32 v66, v192, v66
	ds_write_b32 v67, v66
